# rs cache hit paths no longer drain the next tile's LDS-DMA prefetch (vmcnt(0) dropped where no VGPR load is pending)
# baseline (speedup 1.0000x reference)
; __device__ __forceinline__ unsigned cvt_pk_bf16(float lo, float hi) { unsigned r; asm volatile("v_cvt_pk_bf16_f32 %0, %1, %2" : "=v"(r) : "v"(lo), "v"(hi)); return r; }
;     __device__ __forceinline__ void operator()(const f32x4 (&acc)[2][2][4][2], const Unit& u, int wr, int wc, int fr, int fq) const {
;     ...
;         float rs[2][4]; load_rs<NP>(ssp, row0, fq, rs);
; #pragma unroll
;         for (int ai = 0; ai < 2; ++ai)
; #pragma unroll
;             for (int m = 0; m < 4; ++m) {
;                 const int row = row0 + ai * HALF + m * 16; const float r = rs[ai][m];
;                 const float nrl = r * -1.44269504089f, r2 = r * r;
;                 unsigned pk[4];
; #pragma unroll
;                 for (int q = 0; q < 4; ++q) {
;                     const f32x4 ga = acc[ai][0][m][q >> 1], ua = acc[ai][1][m][q >> 1]; const int e0 = 2 * (q & 1);
;                     const f32x2 g = (f32x2){ga[e0], ga[e0 + 1]}, up = (f32x2){ua[e0], ua[e0 + 1]};
;                     const f32x2 t = g * nrl; f32x2 ex; ex.x = __builtin_amdgcn_exp2f(t.x); ex.y = __builtin_amdgcn_exp2f(t.y);
;                     const f32x2 d = ex + 1.0f; f32x2 rc; rc.x = __builtin_amdgcn_rcpf(d.x); rc.y = __builtin_amdgcn_rcpf(d.y);
;                     const f32x2 o = (g * up) * (rc * r2);
;                     pk[q] = cvt_pk_bf16(o.x, o.y);
;                 }
;                 u32x4 w; w.x = pk[0]; w.y = pk[1]; w.z = pk[2]; w.w = pk[3];
;                 *(u32x4*)(U + (size_t)(row >> 13) * U_SLAB + (size_t)(row & (SEQ - 1)) * U_PITCH + col0) = w;
rsc_hit_3:
	s_lshl_b32 s2, s33, 8
	s_add_i32 s2, s2, s48
	v_or_b32_e32 v144, s2, v146
	v_lshl_or_b32 v154, s57, 7, v148
	v_pk_mul_f32 v[156:157], v[108:109], v[120:121]
	s_ashr_i32 s3, s2, 13
	v_pk_mul_f32 v[158:159], v[106:107], v[114:115]
	v_ashrrev_i32_e32 v155, 31, v154
	v_bitop3_b32 v114, s2, v153, v146 bitop3:0xc8
	s_mul_hi_i32 s19, s3, 0x4400000
	s_mul_i32 s3, s3, 0x4400000
	v_readlane_b32 s24, v235, 44
	v_pk_mul_f32 v[160:161], v[104:105], v[112:113]
	v_lshlrev_b64 v[112:113], 1, v[154:155]
	v_mul_u32_u24_e32 v114, 0xb40, v114
	v_readlane_b32 s25, v235, 45
	s_add_u32 s2, s24, s3
	v_lshlrev_b32_e32 v138, 1, v114
	s_addc_u32 s3, s25, s19
	v_lshl_add_u64 v[114:115], s[2:3], 0, v[138:139]
	v_pk_mul_f32 v[124:125], v[116:117], v[124:125]
	v_pk_mul_f32 v[126:127], v[118:119], v[126:127]
	v_pk_mul_f32 v[122:123], v[110:111], v[122:123]
	v_lshl_add_u64 v[114:115], v[114:115], 0, v[112:113]
	v_pk_mul_f32 v[96:97], v[100:101], v[96:97]
	v_pk_mul_f32 v[98:99], v[102:103], v[98:99]
	v_pk_mul_f32 v[88:89], v[92:93], v[88:89]
	v_pk_mul_f32 v[90:91], v[94:95], v[90:91]
	v_pk_mul_f32 v[80:81], v[84:85], v[80:81]
	v_pk_mul_f32 v[82:83], v[86:87], v[82:83]
	v_pk_mul_f32 v[72:73], v[76:77], v[72:73]
	v_pk_mul_f32 v[74:75], v[78:79], v[74:75]
	v_pk_mul_f32 v[64:65], v[68:69], v[64:65]
	v_pk_mul_f32 v[66:67], v[70:71], v[66:67]
	s_mov_b32 s2, 0x43000
	v_pk_mul_f32 v[56:57], v[60:61], v[56:57]
	v_pk_mul_f32 v[58:59], v[62:63], v[58:59]
	v_pk_mul_f32 v[48:49], v[52:53], v[48:49]
	v_pk_mul_f32 v[50:51], v[54:55], v[50:51]
	v_pk_mul_f32 v[40:41], v[44:45], v[40:41]
	v_pk_mul_f32 v[42:43], v[46:47], v[42:43]
	v_pk_mul_f32 v[32:33], v[36:37], v[32:33]
	v_pk_mul_f32 v[34:35], v[38:39], v[34:35]
	v_pk_mul_f32 v[24:25], v[28:29], v[24:25]
	v_pk_mul_f32 v[26:27], v[30:31], v[26:27]
	v_pk_mul_f32 v[16:17], v[20:21], v[16:17]
	v_pk_mul_f32 v[18:19], v[22:23], v[18:19]
	v_pk_mul_f32 v[8:9], v[12:13], v[8:9]
	v_pk_mul_f32 v[10:11], v[14:15], v[10:11]
	v_pk_mul_f32 v[0:1], v[4:5], v[0:1]
	v_pk_mul_f32 v[2:3], v[6:7], v[2:3]
	v_mov_b32_e32 v164, v240
	s_nop 0
	v_mov_b32_e32 v165, v241
	s_nop 0
	v_mov_b32_e32 v170, v242
	v_mul_f32_e32 v138, 0xbfb8aa3b, v164
	s_nop 0
	v_mov_b32_e32 v121, v246
	v_mul_f32_e32 v162, 0xbfb8aa3b, v165
	v_pk_mul_f32 v[116:117], v[116:117], v[138:139] op_sel_hi:[1,0]
	v_pk_mul_f32 v[108:109], v[108:109], v[138:139] op_sel_hi:[1,0]
	v_pk_mul_f32 v[118:119], v[118:119], v[138:139] op_sel_hi:[1,0]
	v_pk_mul_f32 v[110:111], v[110:111], v[138:139] op_sel_hi:[1,0]
	v_pk_mul_f32 v[104:105], v[104:105], v[162:163] op_sel_hi:[1,0]
	v_exp_f32_e32 v116, v116
	v_exp_f32_e32 v117, v117
	v_exp_f32_e32 v108, v108
	v_exp_f32_e32 v109, v109
	v_pk_mul_f32 v[106:107], v[106:107], v[162:163] op_sel_hi:[1,0]
	v_exp_f32_e32 v118, v118
	v_exp_f32_e32 v119, v119
	v_exp_f32_e32 v110, v110
	v_exp_f32_e32 v111, v111
	v_exp_f32_e32 v104, v104
	v_exp_f32_e32 v105, v105
	v_exp_f32_e32 v106, v106
	v_exp_f32_e32 v107, v107
	s_nop 0
	v_pk_add_f32 v[116:117], v[116:117], 1.0 op_sel_hi:[1,0]
	v_pk_add_f32 v[108:109], v[108:109], 1.0 op_sel_hi:[1,0]
	v_mov_b32_e32 v155, v245
	v_pk_add_f32 v[118:119], v[118:119], 1.0 op_sel_hi:[1,0]
	v_pk_add_f32 v[110:111], v[110:111], 1.0 op_sel_hi:[1,0]
	v_pk_add_f32 v[104:105], v[104:105], 1.0 op_sel_hi:[1,0]
	v_rcp_f32_e32 v116, v116
	v_rcp_f32_e32 v117, v117
	v_rcp_f32_e32 v108, v108
	v_rcp_f32_e32 v109, v109
	v_pk_add_f32 v[106:107], v[106:107], 1.0 op_sel_hi:[1,0]
	v_rcp_f32_e32 v118, v118
	v_rcp_f32_e32 v119, v119
	v_rcp_f32_e32 v110, v110
	v_rcp_f32_e32 v111, v111
	v_rcp_f32_e32 v104, v104
	v_rcp_f32_e32 v105, v105
	v_rcp_f32_e32 v168, v106
	v_rcp_f32_e32 v169, v107
	v_mov_b32_e32 v171, v244
	v_mul_f32_e32 v154, v164, v164
	v_mul_f32_e32 v164, v165, v165
	v_pk_mul_f32 v[106:107], v[154:155], v[116:117] op_sel_hi:[0,1]
	v_pk_mul_f32 v[108:109], v[154:155], v[108:109] op_sel_hi:[0,1]
	v_pk_mul_f32 v[116:117], v[154:155], v[118:119] op_sel_hi:[0,1]
	v_pk_mul_f32 v[110:111], v[154:155], v[110:111] op_sel_hi:[0,1]
	v_pk_mul_f32 v[104:105], v[164:165], v[104:105] op_sel_hi:[0,1]
	v_pk_mul_f32 v[106:107], v[124:125], v[106:107]
	v_pk_mul_f32 v[108:109], v[156:157], v[108:109]
	v_pk_mul_f32 v[166:167], v[100:101], v[162:163] op_sel_hi:[1,0]
	v_pk_mul_f32 v[116:117], v[126:127], v[116:117]
	v_pk_mul_f32 v[110:111], v[122:123], v[110:111]
	v_pk_mul_f32 v[118:119], v[160:161], v[104:105]
	v_cvt_pk_bf16_f32 v104, v106, v107
	v_cvt_pk_bf16_f32 v105, v116, v117
	v_cvt_pk_bf16_f32 v106, v108, v109
	v_cvt_pk_bf16_f32 v107, v110, v111
	v_pk_mul_f32 v[108:109], v[164:165], v[168:169] op_sel_hi:[0,1]
	global_store_dwordx4 v[114:115], v[104:107], off
	v_pk_mul_f32 v[108:109], v[158:159], v[108:109]
	v_mov_b32_e32 v145, v243
	v_exp_f32_e32 v106, v166
	v_exp_f32_e32 v107, v167
	v_cvt_pk_bf16_f32 v104, v118, v119
	v_cvt_pk_bf16_f32 v105, v108, v109
	v_pk_mul_f32 v[108:109], v[102:103], v[162:163] op_sel_hi:[1,0]
	v_pk_add_f32 v[106:107], v[106:107], 1.0 op_sel_hi:[1,0]
	v_exp_f32_e32 v108, v108
	v_exp_f32_e32 v109, v109
	v_rcp_f32_e32 v106, v106
	v_rcp_f32_e32 v107, v107
	v_mov_b32_e32 v120, v247
	s_waitcnt lgkmcnt(0)

; __device__ __forceinline__ unsigned cvt_pk_bf16(float lo, float hi) { unsigned r; asm volatile("v_cvt_pk_bf16_f32 %0, %1, %2" : "=v"(r) : "v"(lo), "v"(hi)); return r; }
;     template <bool GATE> __device__ __forceinline__ void body(const f32x4 (&acc)[2][2][4][2], const Unit& u, int wr, int wc, int fr, int fq) const {
;     ...
;         float rs[2][4]; load_rs<16>(ssp, row0, fq, rs);
; #pragma unroll
;         for (int ai = 0; ai < 2; ++ai)
; #pragma unroll
;             for (int m = 0; m < 4; ++m) {
;                 const int row = row0 + ai * HALF + m * 16; const float r = rs[ai][m], nrl = r * -1.44269504089f;
; #pragma unroll
;                 for (int bj = 0; bj < 2; ++bj) {
;                     unsigned pk[4];
; #pragma unroll
;                     for (int q = 0; q < 4; ++q) {
;                         const f32x4 va = acc[ai][bj][m][q >> 1]; const int e0 = 2 * (q & 1);
;                         const f32x2 v = (f32x2){va[e0], va[e0 + 1]};
;                         f32x2 o;
;                         if (GATE) { const f32x2 t = v * nrl; f32x2 ex; ex.x = __builtin_amdgcn_exp2f(t.x); ex.y = __builtin_amdgcn_exp2f(t.y);
;                             const f32x2 d = ex + 1.0f; o.x = __builtin_amdgcn_rcpf(d.x); o.y = __builtin_amdgcn_rcpf(d.y); }
;                         else o = v * r;
;                         pk[q] = cvt_pk_bf16(o.x, o.y);
;                     }
;                     u32x4 w; w.x = pk[0]; w.y = pk[1]; w.z = pk[2]; w.w = pk[3];
;                     *(u32x4*)(P + (size_t)row * PITCH + col0 + bj * HALF) = w;
;                 }
;             }
;     }
;     __device__ __forceinline__ void operator()(const f32x4 (&acc)[2][2][4][2], const Unit& u, int wr, int wc, int fr, int fq) const {
;         if (u.pn >= 9) body<true>(acc, u, wr, wc, fr, fq); else body<false>(acc, u, wr, wc, fr, fq);
rsc_hit_2:
	v_lshl_add_u32 v186, s33, 8, v193
	v_or_b32_e32 v184, 16, v186
	s_nop 3
	v_or_b32_e32 v182, 32, v186
	v_or_b32_e32 v180, 48, v186
	s_nop 4
	v_add_u32_e32 v178, 0x80, v186
	v_add_u32_e32 v176, 0x90, v186
	v_add_u32_e32 v174, 0xa0, v186
	v_add_u32_e32 v170, 0xb0, v186
	v_and_b32_e32 v172, 64, v201
	v_xor_b32_e32 v171, 16, v201
	v_add_u32_e32 v172, 64, v172
	v_xor_b32_e32 v173, 32, v201
	v_cmp_lt_i32_e32 vcc, v171, v172
	s_cmp_lt_i32 s43, 9
	v_lshl_or_b32 v160, s43, 8, v197
	v_cndmask_b32_e32 v171, v201, v171, vcc
	v_cmp_lt_i32_e32 vcc, v173, v172
	v_lshlrev_b32_e32 v175, 2, v171
	s_nop 2
	v_cndmask_b32_e32 v172, v201, v173, vcc
	s_nop 2
	v_lshlrev_b32_e32 v171, 2, v172
	s_cbranch_scc0 rsc_hitb_2
	v_mov_b32_e32 v208, v240
	v_mov_b32_e32 v210, v241
	v_mov_b32_e32 v212, v242
	v_mov_b32_e32 v214, v243
	v_mov_b32_e32 v194, v244
	v_mov_b32_e32 v192, v245
	v_mov_b32_e32 v190, v246
	v_mov_b32_e32 v188, v247
	s_waitcnt lgkmcnt(0)
	s_branch rsc_joina_2

;     __device__ __forceinline__ void operator()(const f32x4 (&acc)[2][2][4][2], const Unit& u, int wr, int wc, int fr, int fq) const {
;     ...
;         float rs[2][4]; load_rs<NP>(ssp, row0, fq, rs);
; #pragma unroll
;         for (int ai = 0; ai < 2; ++ai)
; #pragma unroll
;             for (int m = 0; m < 4; ++m) {
;                 const int row = row0 + ai * HALF + m * 16; const float r = rs[ai][m];
;                 const float nrl = r * -1.44269504089f, r2 = r * r;
;                 unsigned pk[4];
; #pragma unroll
;                 for (int q = 0; q < 4; ++q) {
;                     const f32x4 ga = acc[ai][0][m][q >> 1], ua = acc[ai][1][m][q >> 1]; const int e0 = 2 * (q & 1);
;                     const f32x2 g = (f32x2){ga[e0], ga[e0 + 1]}, up = (f32x2){ua[e0], ua[e0 + 1]};
;                     const f32x2 t = g * nrl; f32x2 ex; ex.x = __builtin_amdgcn_exp2f(t.x); ex.y = __builtin_amdgcn_exp2f(t.y);
;                     const f32x2 d = ex + 1.0f; f32x2 rc; rc.x = __builtin_amdgcn_rcpf(d.x); rc.y = __builtin_amdgcn_rcpf(d.y);
;                     const f32x2 o = (g * up) * (rc * r2);
rsc_hit_1:
	s_lshl_b32 s2, s41, 8
	s_add_i32 s2, s2, s29
	v_or_b32_e32 v146, s2, v150
	s_nop 4
	v_add_u32_e32 v146, 0x80, v146
	v_pk_mul_f32 v[120:121], v[124:125], v[120:121]
	v_pk_mul_f32 v[122:123], v[126:127], v[122:123]
	v_pk_mul_f32 v[112:113], v[116:117], v[112:113]
	v_pk_mul_f32 v[114:115], v[118:119], v[114:115]
	v_pk_mul_f32 v[104:105], v[108:109], v[104:105]
	s_ashr_i32 s3, s2, 13
	s_mul_hi_i32 s11, s3, 0x4400000
	s_mul_i32 s3, s3, 0x4400000
	v_readlane_b32 s16, v235, 44
	v_lshl_or_b32 v148, s42, 7, v152
	v_readlane_b32 s17, v235, 45
	v_pk_mul_f32 v[106:107], v[110:111], v[106:107]
	v_pk_mul_f32 v[96:97], v[100:101], v[96:97]
	v_pk_mul_f32 v[98:99], v[102:103], v[98:99]
	v_pk_mul_f32 v[88:89], v[92:93], v[88:89]
	v_pk_mul_f32 v[90:91], v[94:95], v[90:91]
	v_pk_mul_f32 v[80:81], v[84:85], v[80:81]
	v_pk_mul_f32 v[82:83], v[86:87], v[82:83]
	v_pk_mul_f32 v[72:73], v[76:77], v[72:73]
	v_pk_mul_f32 v[74:75], v[78:79], v[74:75]
	v_pk_mul_f32 v[64:65], v[68:69], v[64:65]
	v_pk_mul_f32 v[66:67], v[70:71], v[66:67]
	v_pk_mul_f32 v[56:57], v[60:61], v[56:57]
	v_pk_mul_f32 v[58:59], v[62:63], v[58:59]
	v_pk_mul_f32 v[48:49], v[52:53], v[48:49]
	v_pk_mul_f32 v[50:51], v[54:55], v[50:51]
	v_pk_mul_f32 v[40:41], v[44:45], v[40:41]
	v_pk_mul_f32 v[42:43], v[46:47], v[42:43]
	v_pk_mul_f32 v[32:33], v[36:37], v[32:33]
	v_pk_mul_f32 v[34:35], v[38:39], v[34:35]
	v_pk_mul_f32 v[24:25], v[28:29], v[24:25]
	v_pk_mul_f32 v[26:27], v[30:31], v[26:27]
	v_pk_mul_f32 v[16:17], v[20:21], v[16:17]
	v_pk_mul_f32 v[18:19], v[22:23], v[18:19]
	v_pk_mul_f32 v[8:9], v[12:13], v[8:9]
	v_pk_mul_f32 v[10:11], v[14:15], v[10:11]
	v_pk_mul_f32 v[0:1], v[4:5], v[0:1]
	v_pk_mul_f32 v[2:3], v[6:7], v[2:3]
	v_mov_b32_e32 v164, v240
	v_mov_b32_e32 v165, v241
	v_mov_b32_e32 v166, v242
	v_mov_b32_e32 v167, v243
	v_mov_b32_e32 v168, v244
	v_mov_b32_e32 v160, v245
	v_mov_b32_e32 v159, v246
	v_mov_b32_e32 v147, v247
	s_waitcnt lgkmcnt(0)
